# nt on GEMM2/GEMM3 K-loop A-operand LDS-DMA (last-use panels)
# baseline (speedup 1.0000x reference)
.LBB0_448:
	v_add_u32_e32 v1, s78, v210
	ds_read_b128 v[132:135], v1
	ds_read_b128 v[136:139], v1 offset:1024
	ds_read_b128 v[140:143], v1 offset:2048
	ds_read_b128 v[144:147], v1 offset:3072
	v_add_u32_e32 v1, s79, v210
	s_add_u32 s48, s38, s46
	ds_read_b128 v[148:151], v1
	ds_read_b128 v[152:155], v1 offset:1024
	ds_read_b128 v[156:159], v1 offset:2048
	ds_read_b128 v[160:163], v1 offset:3072
	s_addc_u32 s49, s39, s47
	s_add_u32 s48, s48, 0x10000
	s_addc_u32 s49, s49, 0
	s_cmp_eq_u32 s46, 0xf0000
	s_cselect_b32 s64, s81, s48
	s_cselect_b32 s65, s21, s49
	s_cselect_b32 s50, s83, s41
	s_cselect_b32 s51, s19, s86
	s_add_u32 s48, s64, 0x8000
	s_addc_u32 s49, s65, 0
	v_lshl_add_u64 v[2:3], v[204:205], 0, s[46:47]
	s_add_i32 m0, s35, 0xc000
	ds_read_b128 v[164:167], v211
	ds_read_b128 v[168:171], v211 offset:1024
	ds_read_b128 v[172:175], v211 offset:2048
	ds_read_b128 v[176:179], v211 offset:3072
	ds_read_b128 v[180:183], v211 offset:4096
	ds_read_b128 v[184:187], v211 offset:5120
	ds_read_b128 v[212:215], v211 offset:6144
	ds_read_b128 v[216:219], v211 offset:7168
	global_load_lds_dwordx4 v[2:3], off nt
	v_lshl_add_u64 v[2:3], v[206:207], 0, s[46:47]
	s_add_i32 m0, s35, 0xe000
	s_nop 0
	global_load_lds_dwordx4 v[2:3], off nt
	s_waitcnt vmcnt(8)
	s_waitcnt lgkmcnt(0)
	s_barrier
	s_setprio 1
	s_waitcnt lgkmcnt(0)
	v_mfma_f32_16x16x32_bf16 v[128:131], v[132:135], v[164:167], v[128:131]
	v_mfma_f32_16x16x32_bf16 v[124:127], v[140:143], v[164:167], v[124:127]
	v_mfma_f32_16x16x32_bf16 v[112:115], v[132:135], v[172:175], v[112:115]
	v_mfma_f32_16x16x32_bf16 v[108:111], v[140:143], v[172:175], v[108:111]
	v_mfma_f32_16x16x32_bf16 v[96:99], v[132:135], v[180:183], v[96:99]
	v_mfma_f32_16x16x32_bf16 v[92:95], v[140:143], v[180:183], v[92:95]
	v_mfma_f32_16x16x32_bf16 v[80:83], v[132:135], v[212:215], v[80:83]
	v_mfma_f32_16x16x32_bf16 v[76:79], v[140:143], v[212:215], v[76:79]
	v_mfma_f32_16x16x32_bf16 v[128:131], v[136:139], v[168:171], v[128:131]
	v_mfma_f32_16x16x32_bf16 v[124:127], v[144:147], v[168:171], v[124:127]
	v_mfma_f32_16x16x32_bf16 v[112:115], v[136:139], v[176:179], v[112:115]
	v_mfma_f32_16x16x32_bf16 v[108:111], v[144:147], v[176:179], v[108:111]
	v_mfma_f32_16x16x32_bf16 v[96:99], v[136:139], v[184:187], v[96:99]
	v_mfma_f32_16x16x32_bf16 v[92:95], v[144:147], v[184:187], v[92:95]
	v_mfma_f32_16x16x32_bf16 v[80:83], v[136:139], v[216:219], v[80:83]
	v_mfma_f32_16x16x32_bf16 v[76:79], v[144:147], v[216:219], v[76:79]
	s_setprio 0
	s_setprio 1
	v_mfma_f32_16x16x32_bf16 v[120:123], v[148:151], v[164:167], v[120:123]
	v_mfma_f32_16x16x32_bf16 v[116:119], v[156:159], v[164:167], v[116:119]
	v_mfma_f32_16x16x32_bf16 v[104:107], v[148:151], v[172:175], v[104:107]
	v_mfma_f32_16x16x32_bf16 v[100:103], v[156:159], v[172:175], v[100:103]
	v_mfma_f32_16x16x32_bf16 v[88:91], v[148:151], v[180:183], v[88:91]
	v_mfma_f32_16x16x32_bf16 v[84:87], v[156:159], v[180:183], v[84:87]
	v_mfma_f32_16x16x32_bf16 v[72:75], v[148:151], v[212:215], v[72:75]
	v_mfma_f32_16x16x32_bf16 v[68:71], v[156:159], v[212:215], v[68:71]
	v_mfma_f32_16x16x32_bf16 v[120:123], v[152:155], v[168:171], v[120:123]
	v_mfma_f32_16x16x32_bf16 v[116:119], v[160:163], v[168:171], v[116:119]
	v_mfma_f32_16x16x32_bf16 v[104:107], v[152:155], v[176:179], v[104:107]
	v_mfma_f32_16x16x32_bf16 v[100:103], v[160:163], v[176:179], v[100:103]
	v_mfma_f32_16x16x32_bf16 v[88:91], v[152:155], v[184:187], v[88:91]
	v_mfma_f32_16x16x32_bf16 v[84:87], v[160:163], v[184:187], v[84:87]
	v_mfma_f32_16x16x32_bf16 v[72:75], v[152:155], v[216:219], v[72:75]
	v_mfma_f32_16x16x32_bf16 v[68:71], v[160:163], v[216:219], v[68:71]
	s_setprio 0
	s_barrier
	s_add_i32 s88, s78, s34
	s_mov_b32 m0, s88
	ds_read_b128 v[164:167], v211 offset:16384
	ds_read_b128 v[168:171], v211 offset:17408
	ds_read_b128 v[172:175], v211 offset:18432
	ds_read_b128 v[176:179], v211 offset:19456
	ds_read_b128 v[180:183], v211 offset:20480
	ds_read_b128 v[184:187], v211 offset:21504
	ds_read_b128 v[212:215], v211 offset:22528
	ds_read_b128 v[216:219], v211 offset:23552
	global_load_lds_dwordx4 v192, s[50:51]
	s_add_i32 m0, s88, 0x2000
	s_add_u32 s88, s50, 0x80000
	v_lshl_add_u64 v[222:223], s[50:51], 0, v[188:189]
	s_addc_u32 s89, s51, 0
	s_add_i32 s90, s79, s34
	global_load_lds_dwordx4 v[222:223], off
	s_mov_b32 m0, s90
	s_nop 0
	global_load_lds_dwordx4 v192, s[88:89]
	s_add_i32 m0, s90, 0x2000
	s_nop 0
	global_load_lds_dwordx4 v188, s[88:89]
	s_mov_b32 m0, s35
	s_nop 0
	global_load_lds_dwordx4 v194, s[64:65] nt
	s_mov_b32 m0, s56
	s_nop 0
	global_load_lds_dwordx4 v190, s[64:65] nt
	s_waitcnt vmcnt(8)
	s_waitcnt lgkmcnt(0)
	s_barrier
	s_setprio 1
	s_waitcnt lgkmcnt(0)
	v_mfma_f32_16x16x32_bf16 v[64:67], v[132:135], v[164:167], v[64:67]
	v_mfma_f32_16x16x32_bf16 v[60:63], v[140:143], v[164:167], v[60:63]
	v_mfma_f32_16x16x32_bf16 v[48:51], v[132:135], v[172:175], v[48:51]
	v_mfma_f32_16x16x32_bf16 v[44:47], v[140:143], v[172:175], v[44:47]
	v_mfma_f32_16x16x32_bf16 v[32:35], v[132:135], v[180:183], v[32:35]
	v_mfma_f32_16x16x32_bf16 v[28:31], v[140:143], v[180:183], v[28:31]
	v_mfma_f32_16x16x32_bf16 v[16:19], v[132:135], v[212:215], v[16:19]
	v_mfma_f32_16x16x32_bf16 v[12:15], v[140:143], v[212:215], v[12:15]
	v_mfma_f32_16x16x32_bf16 v[64:67], v[136:139], v[168:171], v[64:67]
	v_mfma_f32_16x16x32_bf16 v[60:63], v[144:147], v[168:171], v[60:63]
	v_mfma_f32_16x16x32_bf16 v[48:51], v[136:139], v[176:179], v[48:51]
	v_mfma_f32_16x16x32_bf16 v[44:47], v[144:147], v[176:179], v[44:47]
	v_mfma_f32_16x16x32_bf16 v[32:35], v[136:139], v[184:187], v[32:35]
	v_mfma_f32_16x16x32_bf16 v[28:31], v[144:147], v[184:187], v[28:31]
	v_mfma_f32_16x16x32_bf16 v[16:19], v[136:139], v[216:219], v[16:19]
	v_mfma_f32_16x16x32_bf16 v[12:15], v[144:147], v[216:219], v[12:15]
	s_setprio 0
	s_setprio 1
	v_mfma_f32_16x16x32_bf16 v[56:59], v[148:151], v[164:167], v[56:59]
	v_mfma_f32_16x16x32_bf16 v[52:55], v[156:159], v[164:167], v[52:55]
	v_mfma_f32_16x16x32_bf16 v[40:43], v[148:151], v[172:175], v[40:43]
	v_mfma_f32_16x16x32_bf16 v[36:39], v[156:159], v[172:175], v[36:39]
	v_mfma_f32_16x16x32_bf16 v[24:27], v[148:151], v[180:183], v[24:27]
	v_mfma_f32_16x16x32_bf16 v[20:23], v[156:159], v[180:183], v[20:23]
	v_mfma_f32_16x16x32_bf16 v[8:11], v[148:151], v[212:215], v[8:11]
	v_mfma_f32_16x16x32_bf16 v[2:5], v[156:159], v[212:215], v[4:7]
	v_mfma_f32_16x16x32_bf16 v[56:59], v[152:155], v[168:171], v[56:59]
	v_mfma_f32_16x16x32_bf16 v[52:55], v[160:163], v[168:171], v[52:55]
	v_mfma_f32_16x16x32_bf16 v[40:43], v[152:155], v[176:179], v[40:43]
	v_mfma_f32_16x16x32_bf16 v[36:39], v[160:163], v[176:179], v[36:39]
	v_mfma_f32_16x16x32_bf16 v[24:27], v[152:155], v[184:187], v[24:27]
	v_mfma_f32_16x16x32_bf16 v[20:23], v[160:163], v[184:187], v[20:23]
	v_mfma_f32_16x16x32_bf16 v[8:11], v[152:155], v[216:219], v[8:11]
	v_mfma_f32_16x16x32_bf16 v[2:5], v[160:163], v[216:219], v[2:5]
	s_setprio 0
	s_barrier
	s_add_i32 s88, 0, 0x18000
	v_add_u32_e32 v1, s88, v210
	s_add_i32 s89, 0, 0x1c000
	ds_read_b128 v[132:135], v1
	ds_read_b128 v[136:139], v1 offset:1024
	ds_read_b128 v[140:143], v1 offset:2048
	ds_read_b128 v[144:147], v1 offset:3072
	v_add_u32_e32 v1, s89, v210
	ds_read_b128 v[148:151], v1
	ds_read_b128 v[152:155], v1 offset:1024
	ds_read_b128 v[156:159], v1 offset:2048
	ds_read_b128 v[160:163], v1 offset:3072
	s_add_u32 s64, s64, 0x2000
	s_addc_u32 s65, s65, 0
	s_mov_b32 m0, s57
	ds_read_b128 v[164:167], v211 offset:32768
	ds_read_b128 v[168:171], v211 offset:33792
	ds_read_b128 v[172:175], v211 offset:34816
	ds_read_b128 v[176:179], v211 offset:35840
	ds_read_b128 v[180:183], v211 offset:36864
	ds_read_b128 v[184:187], v211 offset:37888
	ds_read_b128 v[212:215], v211 offset:38912
	ds_read_b128 v[216:219], v211 offset:39936
	global_load_lds_dwordx4 v194, s[64:65] nt
	s_mov_b32 m0, s59
	s_nop 0
	global_load_lds_dwordx4 v190, s[64:65] nt
	s_waitcnt vmcnt(8)
	s_waitcnt lgkmcnt(0)
	s_barrier
	s_setprio 1
	s_waitcnt lgkmcnt(0)
	v_mfma_f32_16x16x32_bf16 v[128:131], v[132:135], v[164:167], v[128:131]
	v_mfma_f32_16x16x32_bf16 v[124:127], v[140:143], v[164:167], v[124:127]
	v_mfma_f32_16x16x32_bf16 v[112:115], v[132:135], v[172:175], v[112:115]
	v_mfma_f32_16x16x32_bf16 v[108:111], v[140:143], v[172:175], v[108:111]
	v_mfma_f32_16x16x32_bf16 v[96:99], v[132:135], v[180:183], v[96:99]
	v_mfma_f32_16x16x32_bf16 v[92:95], v[140:143], v[180:183], v[92:95]
	v_mfma_f32_16x16x32_bf16 v[80:83], v[132:135], v[212:215], v[80:83]
	v_mfma_f32_16x16x32_bf16 v[76:79], v[140:143], v[212:215], v[76:79]
	v_mfma_f32_16x16x32_bf16 v[128:131], v[136:139], v[168:171], v[128:131]
	v_mfma_f32_16x16x32_bf16 v[124:127], v[144:147], v[168:171], v[124:127]
	v_mfma_f32_16x16x32_bf16 v[112:115], v[136:139], v[176:179], v[112:115]
	v_mfma_f32_16x16x32_bf16 v[108:111], v[144:147], v[176:179], v[108:111]
	v_mfma_f32_16x16x32_bf16 v[96:99], v[136:139], v[184:187], v[96:99]
	v_mfma_f32_16x16x32_bf16 v[92:95], v[144:147], v[184:187], v[92:95]
	v_mfma_f32_16x16x32_bf16 v[80:83], v[136:139], v[216:219], v[80:83]
	v_mfma_f32_16x16x32_bf16 v[76:79], v[144:147], v[216:219], v[76:79]
	s_setprio 0
	s_setprio 1
	v_mfma_f32_16x16x32_bf16 v[120:123], v[148:151], v[164:167], v[120:123]
	v_mfma_f32_16x16x32_bf16 v[116:119], v[156:159], v[164:167], v[116:119]
	v_mfma_f32_16x16x32_bf16 v[104:107], v[148:151], v[172:175], v[104:107]
	v_mfma_f32_16x16x32_bf16 v[100:103], v[156:159], v[172:175], v[100:103]
	v_mfma_f32_16x16x32_bf16 v[88:91], v[148:151], v[180:183], v[88:91]
	v_mfma_f32_16x16x32_bf16 v[84:87], v[156:159], v[180:183], v[84:87]
	v_mfma_f32_16x16x32_bf16 v[72:75], v[148:151], v[212:215], v[72:75]
	v_mfma_f32_16x16x32_bf16 v[68:71], v[156:159], v[212:215], v[68:71]
	v_mfma_f32_16x16x32_bf16 v[120:123], v[152:155], v[168:171], v[120:123]
	v_mfma_f32_16x16x32_bf16 v[116:119], v[160:163], v[168:171], v[116:119]
	v_mfma_f32_16x16x32_bf16 v[104:107], v[152:155], v[176:179], v[104:107]
	v_mfma_f32_16x16x32_bf16 v[100:103], v[160:163], v[176:179], v[100:103]
	v_mfma_f32_16x16x32_bf16 v[88:91], v[152:155], v[184:187], v[88:91]
	v_mfma_f32_16x16x32_bf16 v[84:87], v[160:163], v[184:187], v[84:87]
	v_mfma_f32_16x16x32_bf16 v[72:75], v[152:155], v[216:219], v[72:75]
	v_mfma_f32_16x16x32_bf16 v[68:71], v[160:163], v[216:219], v[68:71]
	s_setprio 0
	s_barrier
	s_add_u32 s98, s50, s10
	s_addc_u32 s99, s51, s11
	s_add_i32 s64, s88, s34
	s_mov_b32 m0, s64
	ds_read_b128 v[164:167], v211 offset:49152
	ds_read_b128 v[168:171], v211 offset:50176
	ds_read_b128 v[172:175], v211 offset:51200
	ds_read_b128 v[176:179], v211 offset:52224
	ds_read_b128 v[180:183], v211 offset:53248
	ds_read_b128 v[184:187], v211 offset:54272
	ds_read_b128 v[212:215], v211 offset:55296
	ds_read_b128 v[216:219], v211 offset:56320
	global_load_lds_dwordx4 v192, s[98:99]
	s_add_i32 m0, s64, 0x2000
	s_add_u32 s50, s50, 0x80080
	v_lshl_add_u64 v[6:7], v[222:223], 0, s[10:11]
	s_addc_u32 s51, s51, 0
	s_add_i32 s64, s89, s34
	global_load_lds_dwordx4 v[6:7], off
	s_mov_b32 m0, s64
	s_nop 0
	global_load_lds_dwordx4 v192, s[50:51]
	s_add_i32 m0, s64, 0x2000
	s_nop 0
	global_load_lds_dwordx4 v188, s[50:51]
	s_mov_b32 m0, s74
	s_nop 0
	global_load_lds_dwordx4 v194, s[48:49] nt
	s_mov_b32 m0, s75
	s_nop 0
	global_load_lds_dwordx4 v190, s[48:49] nt
	s_waitcnt vmcnt(8)
	s_waitcnt lgkmcnt(0)
	s_barrier
	s_setprio 1
	s_waitcnt lgkmcnt(0)
	v_mfma_f32_16x16x32_bf16 v[64:67], v[132:135], v[164:167], v[64:67]
	v_mfma_f32_16x16x32_bf16 v[60:63], v[140:143], v[164:167], v[60:63]
	v_mfma_f32_16x16x32_bf16 v[48:51], v[132:135], v[172:175], v[48:51]
	v_mfma_f32_16x16x32_bf16 v[44:47], v[140:143], v[172:175], v[44:47]
	v_mfma_f32_16x16x32_bf16 v[32:35], v[132:135], v[180:183], v[32:35]
	v_mfma_f32_16x16x32_bf16 v[28:31], v[140:143], v[180:183], v[28:31]
	v_mfma_f32_16x16x32_bf16 v[16:19], v[132:135], v[212:215], v[16:19]
	v_mfma_f32_16x16x32_bf16 v[12:15], v[140:143], v[212:215], v[12:15]
	v_mfma_f32_16x16x32_bf16 v[64:67], v[136:139], v[168:171], v[64:67]
	v_mfma_f32_16x16x32_bf16 v[60:63], v[144:147], v[168:171], v[60:63]
	v_mfma_f32_16x16x32_bf16 v[48:51], v[136:139], v[176:179], v[48:51]
	v_mfma_f32_16x16x32_bf16 v[44:47], v[144:147], v[176:179], v[44:47]
	v_mfma_f32_16x16x32_bf16 v[32:35], v[136:139], v[184:187], v[32:35]
	v_mfma_f32_16x16x32_bf16 v[28:31], v[144:147], v[184:187], v[28:31]
	v_mfma_f32_16x16x32_bf16 v[16:19], v[136:139], v[216:219], v[16:19]
	v_mfma_f32_16x16x32_bf16 v[12:15], v[144:147], v[216:219], v[12:15]
	s_setprio 0
	s_setprio 1
	v_mfma_f32_16x16x32_bf16 v[56:59], v[148:151], v[164:167], v[56:59]
	v_mfma_f32_16x16x32_bf16 v[52:55], v[156:159], v[164:167], v[52:55]
	v_mfma_f32_16x16x32_bf16 v[40:43], v[148:151], v[172:175], v[40:43]
	v_mfma_f32_16x16x32_bf16 v[36:39], v[156:159], v[172:175], v[36:39]
	v_mfma_f32_16x16x32_bf16 v[24:27], v[148:151], v[180:183], v[24:27]
	v_mfma_f32_16x16x32_bf16 v[20:23], v[156:159], v[180:183], v[20:23]
	v_mfma_f32_16x16x32_bf16 v[6:9], v[148:151], v[212:215], v[8:11]
	v_mfma_f32_16x16x32_bf16 v[2:5], v[156:159], v[212:215], v[2:5]
	v_mfma_f32_16x16x32_bf16 v[56:59], v[152:155], v[168:171], v[56:59]
	v_mfma_f32_16x16x32_bf16 v[52:55], v[160:163], v[168:171], v[52:55]
	v_mfma_f32_16x16x32_bf16 v[40:43], v[152:155], v[176:179], v[40:43]
	v_mfma_f32_16x16x32_bf16 v[36:39], v[160:163], v[176:179], v[36:39]
	v_mfma_f32_16x16x32_bf16 v[24:27], v[152:155], v[184:187], v[24:27]
	v_mfma_f32_16x16x32_bf16 v[20:23], v[160:163], v[184:187], v[20:23]
	v_mfma_f32_16x16x32_bf16 v[8:11], v[152:155], v[216:219], v[6:9]
	v_mfma_f32_16x16x32_bf16 v[4:7], v[160:163], v[216:219], v[2:5]
	s_setprio 0
	s_barrier
	s_add_i32 s87, s87, 2
	s_add_u32 s41, s41, 0x100
	s_addc_u32 s86, s86, 0
	s_add_u32 s46, s46, 0x10000
	s_addc_u32 s47, s47, 0
	s_cmp_gt_u32 s87, 29
	s_cbranch_scc1 .LBB0_440

.LBB0_507:
	ds_read_b128 v[128:131], v229
	ds_read_b128 v[132:135], v229 offset:1024
	ds_read_b128 v[136:139], v229 offset:2048
	ds_read_b128 v[140:143], v229 offset:3072
	ds_read_b128 v[144:147], v230
	ds_read_b128 v[148:151], v230 offset:1024
	ds_read_b128 v[152:155], v230 offset:2048
	ds_read_b128 v[156:159], v230 offset:3072
	s_add_u32 s44, s42, 0x10000
	s_addc_u32 s45, s43, 0
	s_cmp_eq_u32 s83, 12
	s_cselect_b32 s50, s21, s44
	s_cselect_b32 s51, s8, s45
	s_cselect_b32 s48, s29, s80
	s_cselect_b32 s49, s27, s81
	s_add_u32 s46, s50, 0x8000
	s_addc_u32 s47, s51, 0
	s_add_i32 m0, s23, 0xc000
	ds_read_b128 v[160:163], v231
	ds_read_b128 v[164:167], v231 offset:1024
	ds_read_b128 v[168:171], v231 offset:2048
	ds_read_b128 v[172:175], v231 offset:3072
	ds_read_b128 v[176:179], v231 offset:4096
	ds_read_b128 v[180:183], v231 offset:5120
	ds_read_b128 v[184:187], v231 offset:6144
	ds_read_b128 v[188:191], v231 offset:7168
	global_load_lds_dwordx4 v200, s[42:43] nt
	s_add_i32 m0, s23, 0xe000
	s_nop 0
	global_load_lds_dwordx4 v202, s[42:43] nt
	s_waitcnt vmcnt(8)
	s_waitcnt lgkmcnt(0)
	s_barrier
	s_setprio 1
	s_waitcnt lgkmcnt(0)
	v_mfma_f32_16x16x32_bf16 v[124:127], v[128:131], v[160:163], v[124:127]
	v_mfma_f32_16x16x32_bf16 v[120:123], v[136:139], v[160:163], v[120:123]
	v_mfma_f32_16x16x32_bf16 v[108:111], v[128:131], v[168:171], v[108:111]
	v_mfma_f32_16x16x32_bf16 v[104:107], v[136:139], v[168:171], v[104:107]
	v_mfma_f32_16x16x32_bf16 v[92:95], v[128:131], v[176:179], v[92:95]
	v_mfma_f32_16x16x32_bf16 v[88:91], v[136:139], v[176:179], v[88:91]
	v_mfma_f32_16x16x32_bf16 v[76:79], v[128:131], v[184:187], v[76:79]
	v_mfma_f32_16x16x32_bf16 v[72:75], v[136:139], v[184:187], v[72:75]
	v_mfma_f32_16x16x32_bf16 v[124:127], v[132:135], v[164:167], v[124:127]
	v_mfma_f32_16x16x32_bf16 v[120:123], v[140:143], v[164:167], v[120:123]
	v_mfma_f32_16x16x32_bf16 v[108:111], v[132:135], v[172:175], v[108:111]
	v_mfma_f32_16x16x32_bf16 v[104:107], v[140:143], v[172:175], v[104:107]
	v_mfma_f32_16x16x32_bf16 v[92:95], v[132:135], v[180:183], v[92:95]
	v_mfma_f32_16x16x32_bf16 v[88:91], v[140:143], v[180:183], v[88:91]
	v_mfma_f32_16x16x32_bf16 v[76:79], v[132:135], v[188:191], v[76:79]
	v_mfma_f32_16x16x32_bf16 v[72:75], v[140:143], v[188:191], v[72:75]
	s_setprio 0
	s_setprio 1
	v_mfma_f32_16x16x32_bf16 v[116:119], v[144:147], v[160:163], v[116:119]
	v_mfma_f32_16x16x32_bf16 v[112:115], v[152:155], v[160:163], v[112:115]
	v_mfma_f32_16x16x32_bf16 v[100:103], v[144:147], v[168:171], v[100:103]
	v_mfma_f32_16x16x32_bf16 v[96:99], v[152:155], v[168:171], v[96:99]
	v_mfma_f32_16x16x32_bf16 v[84:87], v[144:147], v[176:179], v[84:87]
	v_mfma_f32_16x16x32_bf16 v[80:83], v[152:155], v[176:179], v[80:83]
	v_mfma_f32_16x16x32_bf16 v[68:71], v[144:147], v[184:187], v[68:71]
	v_mfma_f32_16x16x32_bf16 v[64:67], v[152:155], v[184:187], v[64:67]
	v_mfma_f32_16x16x32_bf16 v[116:119], v[148:151], v[164:167], v[116:119]
	v_mfma_f32_16x16x32_bf16 v[112:115], v[156:159], v[164:167], v[112:115]
	v_mfma_f32_16x16x32_bf16 v[100:103], v[148:151], v[172:175], v[100:103]
	v_mfma_f32_16x16x32_bf16 v[96:99], v[156:159], v[172:175], v[96:99]
	v_mfma_f32_16x16x32_bf16 v[84:87], v[148:151], v[180:183], v[84:87]
	v_mfma_f32_16x16x32_bf16 v[80:83], v[156:159], v[180:183], v[80:83]
	v_mfma_f32_16x16x32_bf16 v[68:71], v[148:151], v[188:191], v[68:71]
	v_mfma_f32_16x16x32_bf16 v[64:67], v[156:159], v[188:191], v[64:67]
	s_setprio 0
	s_barrier
	s_add_i32 s42, s77, s35
	s_mov_b32 m0, s42
	ds_read_b128 v[160:163], v231 offset:16384
	ds_read_b128 v[164:167], v231 offset:17408
	ds_read_b128 v[168:171], v231 offset:18432
	ds_read_b128 v[172:175], v231 offset:19456
	ds_read_b128 v[176:179], v231 offset:20480
	ds_read_b128 v[180:183], v231 offset:21504
	ds_read_b128 v[184:187], v231 offset:22528
	ds_read_b128 v[188:191], v231 offset:23552
	global_load_lds_dwordx4 v194, s[48:49]
	s_add_i32 m0, s42, 0x2000
	s_add_u32 s42, s48, 0x40000
	s_addc_u32 s43, s49, 0
	s_add_i32 s84, s78, s35
	global_load_lds_dwordx4 v198, s[48:49]
	s_mov_b32 m0, s84
	s_nop 0
	global_load_lds_dwordx4 v194, s[42:43]
	s_add_i32 m0, s84, 0x2000
	s_nop 0
	global_load_lds_dwordx4 v198, s[42:43]
	s_mov_b32 m0, s23
	s_nop 0
	global_load_lds_dwordx4 v192, s[50:51] nt
	s_mov_b32 m0, s56
	s_nop 0
	global_load_lds_dwordx4 v196, s[50:51] nt
	s_waitcnt vmcnt(8)
	s_waitcnt lgkmcnt(0)
	s_barrier
	s_setprio 1
	s_waitcnt lgkmcnt(0)
	v_mfma_f32_16x16x32_bf16 v[60:63], v[128:131], v[160:163], v[60:63]
	v_mfma_f32_16x16x32_bf16 v[56:59], v[136:139], v[160:163], v[56:59]
	v_mfma_f32_16x16x32_bf16 v[44:47], v[128:131], v[168:171], v[44:47]
	v_mfma_f32_16x16x32_bf16 v[40:43], v[136:139], v[168:171], v[40:43]
	v_mfma_f32_16x16x32_bf16 v[28:31], v[128:131], v[176:179], v[28:31]
	v_mfma_f32_16x16x32_bf16 v[24:27], v[136:139], v[176:179], v[24:27]
	v_mfma_f32_16x16x32_bf16 v[12:15], v[128:131], v[184:187], v[12:15]
	v_mfma_f32_16x16x32_bf16 v[8:11], v[136:139], v[184:187], v[8:11]
	v_mfma_f32_16x16x32_bf16 v[60:63], v[132:135], v[164:167], v[60:63]
	v_mfma_f32_16x16x32_bf16 v[56:59], v[140:143], v[164:167], v[56:59]
	v_mfma_f32_16x16x32_bf16 v[44:47], v[132:135], v[172:175], v[44:47]
	v_mfma_f32_16x16x32_bf16 v[40:43], v[140:143], v[172:175], v[40:43]
	v_mfma_f32_16x16x32_bf16 v[28:31], v[132:135], v[180:183], v[28:31]
	v_mfma_f32_16x16x32_bf16 v[24:27], v[140:143], v[180:183], v[24:27]
	v_mfma_f32_16x16x32_bf16 v[12:15], v[132:135], v[188:191], v[12:15]
	v_mfma_f32_16x16x32_bf16 v[8:11], v[140:143], v[188:191], v[8:11]
	s_setprio 0
	s_setprio 1
	v_mfma_f32_16x16x32_bf16 v[52:55], v[144:147], v[160:163], v[52:55]
	v_mfma_f32_16x16x32_bf16 v[48:51], v[152:155], v[160:163], v[48:51]
	v_mfma_f32_16x16x32_bf16 v[36:39], v[144:147], v[168:171], v[36:39]
	v_mfma_f32_16x16x32_bf16 v[32:35], v[152:155], v[168:171], v[32:35]
	v_mfma_f32_16x16x32_bf16 v[20:23], v[144:147], v[176:179], v[20:23]
	v_mfma_f32_16x16x32_bf16 v[16:19], v[152:155], v[176:179], v[16:19]
	v_mfma_f32_16x16x32_bf16 v[4:7], v[144:147], v[184:187], v[4:7]
	v_mfma_f32_16x16x32_bf16 v[0:3], v[152:155], v[184:187], v[0:3]
	v_mfma_f32_16x16x32_bf16 v[52:55], v[148:151], v[164:167], v[52:55]
	v_mfma_f32_16x16x32_bf16 v[48:51], v[156:159], v[164:167], v[48:51]
	v_mfma_f32_16x16x32_bf16 v[36:39], v[148:151], v[172:175], v[36:39]
	v_mfma_f32_16x16x32_bf16 v[32:35], v[156:159], v[172:175], v[32:35]
	v_mfma_f32_16x16x32_bf16 v[20:23], v[148:151], v[180:183], v[20:23]
	v_mfma_f32_16x16x32_bf16 v[16:19], v[156:159], v[180:183], v[16:19]
	v_mfma_f32_16x16x32_bf16 v[4:7], v[148:151], v[188:191], v[4:7]
	v_mfma_f32_16x16x32_bf16 v[0:3], v[156:159], v[188:191], v[0:3]
	s_setprio 0
	s_barrier
	s_add_i32 s84, 0, 0x18000
	s_add_i32 s85, 0, 0x1c000
	v_add_u32_e32 v140, s84, v228
	v_add_u32_e32 v156, s85, v228
	ds_read_b128 v[128:131], v140
	ds_read_b128 v[132:135], v140 offset:1024
	ds_read_b128 v[136:139], v140 offset:2048
	ds_read_b128 v[140:143], v140 offset:3072
	ds_read_b128 v[144:147], v156
	ds_read_b128 v[148:151], v156 offset:1024
	ds_read_b128 v[152:155], v156 offset:2048
	ds_read_b128 v[156:159], v156 offset:3072
	s_add_u32 s42, s50, 0x2000
	s_addc_u32 s43, s51, 0
	s_mov_b32 m0, s57
	ds_read_b128 v[160:163], v231 offset:32768
	ds_read_b128 v[164:167], v231 offset:33792
	ds_read_b128 v[168:171], v231 offset:34816
	ds_read_b128 v[172:175], v231 offset:35840
	ds_read_b128 v[176:179], v231 offset:36864
	ds_read_b128 v[180:183], v231 offset:37888
	ds_read_b128 v[184:187], v231 offset:38912
	ds_read_b128 v[188:191], v231 offset:39936
	global_load_lds_dwordx4 v192, s[42:43] nt
	s_mov_b32 m0, s59
	s_nop 0
	global_load_lds_dwordx4 v196, s[42:43] nt
	s_waitcnt vmcnt(8)
	s_waitcnt lgkmcnt(0)
	s_barrier
	s_setprio 1
	s_waitcnt lgkmcnt(0)
	v_mfma_f32_16x16x32_bf16 v[124:127], v[128:131], v[160:163], v[124:127]
	v_mfma_f32_16x16x32_bf16 v[120:123], v[136:139], v[160:163], v[120:123]
	v_mfma_f32_16x16x32_bf16 v[108:111], v[128:131], v[168:171], v[108:111]
	v_mfma_f32_16x16x32_bf16 v[104:107], v[136:139], v[168:171], v[104:107]
	v_mfma_f32_16x16x32_bf16 v[92:95], v[128:131], v[176:179], v[92:95]
	v_mfma_f32_16x16x32_bf16 v[88:91], v[136:139], v[176:179], v[88:91]
	v_mfma_f32_16x16x32_bf16 v[76:79], v[128:131], v[184:187], v[76:79]
	v_mfma_f32_16x16x32_bf16 v[72:75], v[136:139], v[184:187], v[72:75]
	v_mfma_f32_16x16x32_bf16 v[124:127], v[132:135], v[164:167], v[124:127]
	v_mfma_f32_16x16x32_bf16 v[120:123], v[140:143], v[164:167], v[120:123]
	v_mfma_f32_16x16x32_bf16 v[108:111], v[132:135], v[172:175], v[108:111]
	v_mfma_f32_16x16x32_bf16 v[104:107], v[140:143], v[172:175], v[104:107]
	v_mfma_f32_16x16x32_bf16 v[92:95], v[132:135], v[180:183], v[92:95]
	v_mfma_f32_16x16x32_bf16 v[88:91], v[140:143], v[180:183], v[88:91]
	v_mfma_f32_16x16x32_bf16 v[76:79], v[132:135], v[188:191], v[76:79]
	v_mfma_f32_16x16x32_bf16 v[72:75], v[140:143], v[188:191], v[72:75]
	s_setprio 0
	s_setprio 1
	v_mfma_f32_16x16x32_bf16 v[116:119], v[144:147], v[160:163], v[116:119]
	v_mfma_f32_16x16x32_bf16 v[112:115], v[152:155], v[160:163], v[112:115]
	v_mfma_f32_16x16x32_bf16 v[100:103], v[144:147], v[168:171], v[100:103]
	v_mfma_f32_16x16x32_bf16 v[96:99], v[152:155], v[168:171], v[96:99]
	v_mfma_f32_16x16x32_bf16 v[84:87], v[144:147], v[176:179], v[84:87]
	v_mfma_f32_16x16x32_bf16 v[80:83], v[152:155], v[176:179], v[80:83]
	v_mfma_f32_16x16x32_bf16 v[68:71], v[144:147], v[184:187], v[68:71]
	v_mfma_f32_16x16x32_bf16 v[64:67], v[152:155], v[184:187], v[64:67]
	v_mfma_f32_16x16x32_bf16 v[116:119], v[148:151], v[164:167], v[116:119]
	v_mfma_f32_16x16x32_bf16 v[112:115], v[156:159], v[164:167], v[112:115]
	v_mfma_f32_16x16x32_bf16 v[100:103], v[148:151], v[172:175], v[100:103]
	v_mfma_f32_16x16x32_bf16 v[96:99], v[156:159], v[172:175], v[96:99]
	v_mfma_f32_16x16x32_bf16 v[84:87], v[148:151], v[180:183], v[84:87]
	v_mfma_f32_16x16x32_bf16 v[80:83], v[156:159], v[180:183], v[80:83]
	v_mfma_f32_16x16x32_bf16 v[68:71], v[148:151], v[188:191], v[68:71]
	v_mfma_f32_16x16x32_bf16 v[64:67], v[156:159], v[188:191], v[64:67]
	s_setprio 0
	s_barrier
	s_add_u32 s98, s48, s16
	s_addc_u32 s99, s49, s17
	s_add_i32 s42, s84, s35
	s_mov_b32 m0, s42
	ds_read_b128 v[160:163], v231 offset:49152
	ds_read_b128 v[164:167], v231 offset:50176
	ds_read_b128 v[168:171], v231 offset:51200
	ds_read_b128 v[172:175], v231 offset:52224
	ds_read_b128 v[176:179], v231 offset:53248
	ds_read_b128 v[180:183], v231 offset:54272
	ds_read_b128 v[184:187], v231 offset:55296
	ds_read_b128 v[188:191], v231 offset:56320
	global_load_lds_dwordx4 v194, s[98:99]
	s_add_i32 m0, s42, 0x2000
	s_add_u32 s42, s48, 0x40080
	s_addc_u32 s43, s49, 0
	s_add_i32 s48, s85, s35
	global_load_lds_dwordx4 v198, s[98:99]
	s_mov_b32 m0, s48
	s_nop 0
	global_load_lds_dwordx4 v194, s[42:43]
	s_add_i32 m0, s48, 0x2000
	s_nop 0
	global_load_lds_dwordx4 v198, s[42:43]
	s_mov_b32 m0, s75
	s_nop 0
	global_load_lds_dwordx4 v192, s[46:47] nt
	s_mov_b32 m0, s76
	s_nop 0
	global_load_lds_dwordx4 v196, s[46:47] nt
	s_waitcnt vmcnt(8)
	s_waitcnt lgkmcnt(0)
	s_barrier
	s_setprio 1
	s_waitcnt lgkmcnt(0)
	v_mfma_f32_16x16x32_bf16 v[60:63], v[128:131], v[160:163], v[60:63]
	v_mfma_f32_16x16x32_bf16 v[56:59], v[136:139], v[160:163], v[56:59]
	v_mfma_f32_16x16x32_bf16 v[44:47], v[128:131], v[168:171], v[44:47]
	v_mfma_f32_16x16x32_bf16 v[40:43], v[136:139], v[168:171], v[40:43]
	v_mfma_f32_16x16x32_bf16 v[28:31], v[128:131], v[176:179], v[28:31]
	v_mfma_f32_16x16x32_bf16 v[24:27], v[136:139], v[176:179], v[24:27]
	v_mfma_f32_16x16x32_bf16 v[12:15], v[128:131], v[184:187], v[12:15]
	v_mfma_f32_16x16x32_bf16 v[8:11], v[136:139], v[184:187], v[8:11]
	v_mfma_f32_16x16x32_bf16 v[60:63], v[132:135], v[164:167], v[60:63]
	v_mfma_f32_16x16x32_bf16 v[56:59], v[140:143], v[164:167], v[56:59]
	v_mfma_f32_16x16x32_bf16 v[44:47], v[132:135], v[172:175], v[44:47]
	v_mfma_f32_16x16x32_bf16 v[40:43], v[140:143], v[172:175], v[40:43]
	v_mfma_f32_16x16x32_bf16 v[28:31], v[132:135], v[180:183], v[28:31]
	v_mfma_f32_16x16x32_bf16 v[24:27], v[140:143], v[180:183], v[24:27]
	v_mfma_f32_16x16x32_bf16 v[12:15], v[132:135], v[188:191], v[12:15]
	v_mfma_f32_16x16x32_bf16 v[8:11], v[140:143], v[188:191], v[8:11]
	s_setprio 0
	s_setprio 1
	v_mfma_f32_16x16x32_bf16 v[52:55], v[144:147], v[160:163], v[52:55]
	v_mfma_f32_16x16x32_bf16 v[48:51], v[152:155], v[160:163], v[48:51]
	v_mfma_f32_16x16x32_bf16 v[36:39], v[144:147], v[168:171], v[36:39]
	v_mfma_f32_16x16x32_bf16 v[32:35], v[152:155], v[168:171], v[32:35]
	v_mfma_f32_16x16x32_bf16 v[20:23], v[144:147], v[176:179], v[20:23]
	v_mfma_f32_16x16x32_bf16 v[16:19], v[152:155], v[176:179], v[16:19]
	v_mfma_f32_16x16x32_bf16 v[4:7], v[144:147], v[184:187], v[4:7]
	v_mfma_f32_16x16x32_bf16 v[0:3], v[152:155], v[184:187], v[0:3]
	v_mfma_f32_16x16x32_bf16 v[52:55], v[148:151], v[164:167], v[52:55]
	v_mfma_f32_16x16x32_bf16 v[48:51], v[156:159], v[164:167], v[48:51]
	v_mfma_f32_16x16x32_bf16 v[36:39], v[148:151], v[172:175], v[36:39]
	v_mfma_f32_16x16x32_bf16 v[32:35], v[156:159], v[172:175], v[32:35]
	v_mfma_f32_16x16x32_bf16 v[20:23], v[148:151], v[180:183], v[20:23]
	v_mfma_f32_16x16x32_bf16 v[16:19], v[156:159], v[180:183], v[16:19]
	v_mfma_f32_16x16x32_bf16 v[4:7], v[148:151], v[188:191], v[4:7]
	v_mfma_f32_16x16x32_bf16 v[0:3], v[156:159], v[188:191], v[0:3]
	s_setprio 0
	s_barrier
	s_add_i32 s83, s83, 2
	s_add_u32 s80, s80, 0x100
	s_addc_u32 s81, s81, 0
	s_cmp_gt_u32 s83, 13
	s_mov_b64 s[42:43], s[44:45]
	s_cbranch_scc0 .LBB0_507
	v_mov_b32_e32 v233, v227
	v_mov_b32_e32 v144, v226
	s_lshl_b32 s8, s22, 8
	s_or_b32 s8, s8, s73
	v_lshlrev_b32_e32 v208, 3, v233
	v_add_u32_e32 v128, s8, v208
	s_lshr_b32 s8, s20, 4
	s_mul_i32 s42, s8, 0x1800
	s_ashr_i32 s43, s42, 31
	s_lshl_b64 s[42:43], s[42:43], 2
	s_add_u32 s42, s69, s42
	v_ashrrev_i32_e32 v129, 31, v128
	v_add_u32_e32 v210, s72, v144
	s_addc_u32 s43, s70, s43
	v_lshlrev_b64 v[212:213], 2, v[128:129]
	v_lshl_add_u32 v216, s20, 8, v210
	v_lshl_add_u64 v[214:215], s[42:43], 0, v[212:213]
	v_ashrrev_i32_e32 v217, 31, v216
	v_add_co_u32_e32 v128, vcc, s65, v214
	v_lshl_add_u64 v[218:219], s[36:37], 0, v[212:213]
	v_lshlrev_b64 v[144:145], 12, v[216:217]
	v_add_u32_e32 v224, 16, v216
	v_lshl_add_u64 v[132:133], v[214:215], 0, s[10:11]
	v_addc_co_u32_e32 v129, vcc, 0, v215, vcc
	v_lshl_add_u64 v[144:145], v[218:219], 0, v[144:145]
	v_ashrrev_i32_e32 v225, 31, v224
	global_load_dwordx4 v[140:143], v[128:129], off nt
	s_nop 0
	global_load_dwordx4 v[128:131], v[132:133], off offset:528 nt
	global_load_dwordx4 v[136:139], v[132:133], off offset:16 nt
	s_nop 0
	global_load_dwordx4 v[132:135], v[132:133], off offset:512 nt
	s_nop 0
	global_load_dwordx4 v[234:237], v[144:145], off offset:16 nt
	global_load_dwordx4 v[238:241], v[144:145], off nt
	global_load_dwordx4 v[242:245], v[144:145], off offset:528 nt
	global_load_dwordx4 v[246:249], v[144:145], off offset:512 nt
	v_lshlrev_b64 v[144:145], 12, v[224:225]
	v_add_u32_e32 v222, 32, v216
	v_lshl_add_u64 v[144:145], v[218:219], 0, v[144:145]
	v_ashrrev_i32_e32 v223, 31, v222
	global_load_dwordx4 v[184:187], v[144:145], off offset:16 nt
	global_load_dwordx4 v[188:191], v[144:145], off nt
	global_load_dwordx4 v[176:179], v[144:145], off offset:528 nt
	global_load_dwordx4 v[180:183], v[144:145], off offset:512 nt
	v_lshlrev_b64 v[144:145], 12, v[222:223]
	v_add_u32_e32 v220, 48, v216
	v_lshl_add_u64 v[144:145], v[218:219], 0, v[144:145]
	v_ashrrev_i32_e32 v221, 31, v220
	global_load_dwordx4 v[168:171], v[144:145], off offset:16 nt
	global_load_dwordx4 v[172:175], v[144:145], off nt
	global_load_dwordx4 v[160:163], v[144:145], off offset:528 nt
	global_load_dwordx4 v[164:167], v[144:145], off offset:512 nt
	v_lshlrev_b64 v[144:145], 12, v[220:221]
	v_lshl_add_u64 v[148:149], v[218:219], 0, v[144:145]
	global_load_dwordx4 v[152:155], v[148:149], off offset:16 nt
	global_load_dwordx4 v[156:159], v[148:149], off nt
	global_load_dwordx4 v[144:147], v[148:149], off offset:528 nt
	s_nop 0
	global_load_dwordx4 v[148:151], v[148:149], off offset:512 nt
	v_and_b32_e32 v211, 64, v232
	v_xor_b32_e32 v209, 16, v232
	v_add_u32_e32 v211, 64, v211
	v_cmp_lt_i32_e32 vcc, v209, v211
	v_xor_b32_e32 v250, 32, v232
	s_lshl_b32 s42, s22, 2
	v_cndmask_b32_e32 v209, v232, v209, vcc
	v_cmp_lt_i32_e32 vcc, v250, v211
	v_lshlrev_b32_e32 v209, 2, v209
	s_ashr_i32 s43, s42, 31
	v_cndmask_b32_e32 v211, v232, v250, vcc
	v_lshlrev_b32_e32 v211, 2, v211
	v_cmp_eq_u32_e32 vcc, 0, v233
	s_waitcnt vmcnt(0)
	v_pk_fma_f32 v[126:127], v[126:127], v[142:143], v[240:241]
	v_pk_fma_f32 v[124:125], v[124:125], v[140:141], v[238:239]
	v_pk_fma_f32 v[120:121], v[120:121], v[136:137], v[234:235]
	v_mul_f32_e32 v233, v125, v125
	v_mul_f32_e32 v234, v127, v127
	v_fmac_f32_e32 v233, v124, v124
	v_fmac_f32_e32 v234, v126, v126
	v_add_f32_e32 v233, v233, v234
	v_mul_f32_e32 v234, v121, v121
	v_pk_fma_f32 v[122:123], v[122:123], v[138:139], v[236:237]
	v_fmac_f32_e32 v234, v120, v120
	v_add_f32_e32 v233, v233, v234
	v_mul_f32_e32 v234, v123, v123
	v_fmac_f32_e32 v234, v122, v122
	v_pk_fma_f32 v[118:119], v[118:119], v[134:135], v[248:249]
	v_pk_fma_f32 v[116:117], v[116:117], v[132:133], v[246:247]
	v_add_f32_e32 v233, v234, v233
	v_mul_f32_e32 v234, v117, v117
	v_mul_f32_e32 v235, v119, v119
	v_pk_fma_f32 v[112:113], v[112:113], v[128:129], v[242:243]
	v_fmac_f32_e32 v234, v116, v116
	v_fmac_f32_e32 v235, v118, v118
	v_add_f32_e32 v234, v234, v235
	v_mul_f32_e32 v235, v113, v113
	v_pk_fma_f32 v[114:115], v[114:115], v[130:131], v[244:245]
	v_fmac_f32_e32 v235, v112, v112
	v_add_f32_e32 v234, v234, v235
	v_mul_f32_e32 v235, v115, v115
	v_fmac_f32_e32 v235, v114, v114
	v_add_f32_e32 v234, v235, v234
	v_add_f32_e32 v233, v233, v234
	ds_bpermute_b32 v234, v209, v233
	s_waitcnt lgkmcnt(0)
	v_add_f32_e32 v233, v233, v234
	ds_bpermute_b32 v234, v211, v233
	s_and_saveexec_b64 s[44:45], vcc
	s_cbranch_execz .LBB0_510
	v_lshlrev_b64 v[236:237], 6, v[216:217]
	v_lshl_add_u64 v[236:237], s[12:13], 0, v[236:237]
	v_lshl_add_u64 v[236:237], s[42:43], 2, v[236:237]
	s_lshl_b32 s8, s71, 2
	v_lshl_add_u64 v[236:237], v[236:237], 0, s[8:9]
	s_waitcnt lgkmcnt(0)
	v_add_f32_e32 v217, v233, v234
	global_store_dword v[236:237], v217, off
